# out-proj layer-1 post-loop: pipelined fragment reads; in-place residual epilogue loads batched 8 rows ahead with counted vmcnt (same treatment layer 0 already had)
# baseline (speedup 1.0000x reference)
.Lyb_wr_done_L1:
	s_waitcnt lgkmcnt(8)
	v_mfma_f32_32x32x16_bf16 v[16:31], v[186:189], v[150:153], v[16:31]
	s_waitcnt lgkmcnt(0)
	s_barrier
	v_mfma_f32_32x32x16_bf16 v[0:15], v[186:189], v[158:161], v[0:15]
	s_cbranch_scc1 .LBB0_992
	s_mov_b32 s0, 0x10000
	v_add3_u32 v194, v140, v138, 16
	v_add3_u32 v195, v139, v138, 16
	v_add3_u32 v197, v143, v195, s0
	v_add3_u32 v196, v143, v194, s0
	ds_read_b128 v[178:181], v197 offset:32768
	ds_read_b128 v[182:185], v197 offset:36864
	ds_read_b128 v[144:147], v196
	ds_read_b128 v[148:151], v196 offset:4096
	ds_read_b128 v[152:155], v196 offset:8192
	ds_read_b128 v[156:159], v196 offset:12288
	v_add3_u32 v196, v142, v194, s0
	ds_read_b128 v[160:163], v196
	v_add3_u32 v197, v142, v195, s0
	ds_read_b128 v[186:189], v197 offset:32768
	ds_read_b128 v[190:193], v197 offset:36864
	s_waitcnt lgkmcnt(6)
	v_mfma_f32_32x32x16_bf16 v[112:127], v[144:147], v[178:181], v[112:127]
	v_mfma_f32_32x32x16_bf16 v[96:111], v[144:147], v[182:185], v[96:111]
	ds_read_b128 v[144:147], v196 offset:4096
	s_waitcnt lgkmcnt(6)
	v_mfma_f32_32x32x16_bf16 v[80:95], v[148:151], v[178:181], v[80:95]
	v_mfma_f32_32x32x16_bf16 v[64:79], v[148:151], v[182:185], v[64:79]
	ds_read_b128 v[148:151], v196 offset:8192
	s_waitcnt lgkmcnt(6)
	v_mfma_f32_32x32x16_bf16 v[48:63], v[152:155], v[178:181], v[48:63]
	v_mfma_f32_32x32x16_bf16 v[32:47], v[152:155], v[182:185], v[32:47]
	ds_read_b128 v[152:155], v196 offset:12288
	s_waitcnt lgkmcnt(6)
	v_mfma_f32_32x32x16_bf16 v[16:31], v[156:159], v[178:181], v[16:31]
	v_mfma_f32_32x32x16_bf16 v[0:15], v[156:159], v[182:185], v[0:15]
	v_add3_u32 v196, v141, v194, s0
	ds_read_b128 v[156:159], v196
	v_add3_u32 v197, v141, v195, s0
	ds_read_b128 v[178:181], v197 offset:32768
	ds_read_b128 v[182:185], v197 offset:36864
	s_waitcnt lgkmcnt(6)
	v_mfma_f32_32x32x16_bf16 v[112:127], v[160:163], v[186:189], v[112:127]
	v_mfma_f32_32x32x16_bf16 v[96:111], v[160:163], v[190:193], v[96:111]
	ds_read_b128 v[160:163], v196 offset:4096
	s_waitcnt lgkmcnt(6)
	v_mfma_f32_32x32x16_bf16 v[80:95], v[144:147], v[186:189], v[80:95]
	v_mfma_f32_32x32x16_bf16 v[64:79], v[144:147], v[190:193], v[64:79]
	ds_read_b128 v[144:147], v196 offset:8192
	s_waitcnt lgkmcnt(6)
	v_mfma_f32_32x32x16_bf16 v[48:63], v[148:151], v[186:189], v[48:63]
	v_mfma_f32_32x32x16_bf16 v[32:47], v[148:151], v[190:193], v[32:47]
	ds_read_b128 v[148:151], v196 offset:12288
	s_waitcnt lgkmcnt(6)
	v_mfma_f32_32x32x16_bf16 v[16:31], v[152:155], v[186:189], v[16:31]
	v_mfma_f32_32x32x16_bf16 v[0:15], v[152:155], v[190:193], v[0:15]
	v_add3_u32 v196, v170, v194, s0
	ds_read_b128 v[152:155], v196
	v_add3_u32 v197, v170, v195, s0
	ds_read_b128 v[186:189], v197 offset:32768
	ds_read_b128 v[190:193], v197 offset:36864
	s_waitcnt lgkmcnt(6)
	v_mfma_f32_32x32x16_bf16 v[112:127], v[156:159], v[178:181], v[112:127]
	v_mfma_f32_32x32x16_bf16 v[96:111], v[156:159], v[182:185], v[96:111]
	ds_read_b128 v[156:159], v196 offset:4096
	s_waitcnt lgkmcnt(6)
	v_mfma_f32_32x32x16_bf16 v[80:95], v[160:163], v[178:181], v[80:95]
	v_mfma_f32_32x32x16_bf16 v[64:79], v[160:163], v[182:185], v[64:79]
	ds_read_b128 v[160:163], v196 offset:8192
	s_waitcnt lgkmcnt(6)
	v_mfma_f32_32x32x16_bf16 v[48:63], v[144:147], v[178:181], v[48:63]
	v_mfma_f32_32x32x16_bf16 v[32:47], v[144:147], v[182:185], v[32:47]
	ds_read_b128 v[144:147], v196 offset:12288
	s_waitcnt lgkmcnt(6)
	v_mfma_f32_32x32x16_bf16 v[16:31], v[148:151], v[178:181], v[16:31]
	v_mfma_f32_32x32x16_bf16 v[0:15], v[148:151], v[182:185], v[0:15]
	s_waitcnt lgkmcnt(3)
	v_mfma_f32_32x32x16_bf16 v[112:127], v[152:155], v[186:189], v[112:127]
	v_mfma_f32_32x32x16_bf16 v[96:111], v[152:155], v[190:193], v[96:111]
	s_waitcnt lgkmcnt(2)
	v_mfma_f32_32x32x16_bf16 v[80:95], v[156:159], v[186:189], v[80:95]
	v_mfma_f32_32x32x16_bf16 v[64:79], v[156:159], v[190:193], v[64:79]
	s_waitcnt lgkmcnt(1)
	v_mfma_f32_32x32x16_bf16 v[48:63], v[160:163], v[186:189], v[48:63]
	v_mfma_f32_32x32x16_bf16 v[32:47], v[160:163], v[190:193], v[32:47]
	s_waitcnt lgkmcnt(0)
	v_mfma_f32_32x32x16_bf16 v[16:31], v[144:147], v[186:189], v[16:31]
	v_mfma_f32_32x32x16_bf16 v[0:15], v[144:147], v[190:193], v[0:15]
	s_waitcnt lgkmcnt(0)
	s_barrier
	s_add_i32 s2, s2, s50
	s_add_i32 s9, s9, s10
	v_lshl_or_b32 v164, v169, 6, s20
	v_lshl_add_u32 v166, v166, 7, s19
	v_lshl_or_b32 v166, v168, 2, v166
	v_or_b32_e32 v168, v164, v167
	v_lshl_add_u32 v128, v166, 10, v168
	v_lshlrev_b32_e32 v128, 2, v128
	global_load_dword v144, v128, s[84:85]
	global_load_dword v145, v128, s[84:85] offset:128
	v_add_u32_e32 v129, 0x1000, v128
	global_load_dword v146, v129, s[84:85]
	global_load_dword v147, v129, s[84:85] offset:128
	v_add_u32_e32 v130, 0x1000, v129
	global_load_dword v148, v130, s[84:85]
	global_load_dword v149, v130, s[84:85] offset:128
	v_add_u32_e32 v131, 0x1000, v130
	global_load_dword v150, v131, s[84:85]
	global_load_dword v151, v131, s[84:85] offset:128
	v_add_u32_e32 v132, 0x5000, v131
	global_load_dword v152, v132, s[84:85]
	global_load_dword v153, v132, s[84:85] offset:128
	v_add_u32_e32 v133, 0x1000, v132
	global_load_dword v154, v133, s[84:85]
	global_load_dword v155, v133, s[84:85] offset:128
	v_add_u32_e32 v134, 0x1000, v133
	global_load_dword v156, v134, s[84:85]
	global_load_dword v157, v134, s[84:85] offset:128
	v_add_u32_e32 v135, 0x1000, v134
	global_load_dword v158, v135, s[84:85]
	global_load_dword v159, v135, s[84:85] offset:128
	v_add_u32_e32 v136, 0x5000, v135
	global_load_dword v178, v136, s[84:85]
	global_load_dword v179, v136, s[84:85] offset:128
	v_add_u32_e32 v137, 0x1000, v136
	global_load_dword v180, v137, s[84:85]
	global_load_dword v181, v137, s[84:85] offset:128
	v_add_u32_e32 v198, 0x1000, v137
	global_load_dword v182, v198, s[84:85]
	global_load_dword v183, v198, s[84:85] offset:128
	v_add_u32_e32 v199, 0x1000, v198
	global_load_dword v184, v199, s[84:85]
	global_load_dword v185, v199, s[84:85] offset:128
	v_add_u32_e32 v200, 0x5000, v199
	global_load_dword v186, v200, s[84:85]
	global_load_dword v187, v200, s[84:85] offset:128
	v_add_u32_e32 v201, 0x1000, v200
	global_load_dword v188, v201, s[84:85]
	global_load_dword v189, v201, s[84:85] offset:128
	v_add_u32_e32 v202, 0x1000, v201
	global_load_dword v190, v202, s[84:85]
	global_load_dword v191, v202, s[84:85] offset:128
	v_add_u32_e32 v203, 0x1000, v202
	global_load_dword v192, v203, s[84:85]
	global_load_dword v193, v203, s[84:85] offset:128
	s_waitcnt vmcnt(16)
	v_add_f32_e32 v144, v112, v144
	v_add_f32_e32 v145, v96, v145
	global_store_dword v128, v144, s[84:85]
	global_store_dword v128, v145, s[84:85] offset:128
	v_add_f32_e32 v146, v113, v146
	v_add_f32_e32 v147, v97, v147
	global_store_dword v129, v146, s[84:85]
	global_store_dword v129, v147, s[84:85] offset:128
	v_add_f32_e32 v148, v114, v148
	v_add_f32_e32 v149, v98, v149
	global_store_dword v130, v148, s[84:85]
	global_store_dword v130, v149, s[84:85] offset:128
	v_add_f32_e32 v150, v115, v150
	v_add_f32_e32 v151, v99, v151
	global_store_dword v131, v150, s[84:85]
	global_store_dword v131, v151, s[84:85] offset:128
	v_add_f32_e32 v152, v116, v152
	v_add_f32_e32 v153, v100, v153
	global_store_dword v132, v152, s[84:85]
	global_store_dword v132, v153, s[84:85] offset:128
	v_add_f32_e32 v154, v117, v154
	v_add_f32_e32 v155, v101, v155
	global_store_dword v133, v154, s[84:85]
	global_store_dword v133, v155, s[84:85] offset:128
	v_add_f32_e32 v156, v118, v156
	v_add_f32_e32 v157, v102, v157
	global_store_dword v134, v156, s[84:85]
	global_store_dword v134, v157, s[84:85] offset:128
	v_add_f32_e32 v158, v119, v158
	v_add_f32_e32 v159, v103, v159
	global_store_dword v135, v158, s[84:85]
	global_store_dword v135, v159, s[84:85] offset:128
	v_add_u32_e32 v128, 0x5000, v203
	global_load_dword v144, v128, s[84:85]
	global_load_dword v145, v128, s[84:85] offset:128
	v_add_u32_e32 v129, 0x1000, v128
	global_load_dword v146, v129, s[84:85]
	global_load_dword v147, v129, s[84:85] offset:128
	v_add_u32_e32 v130, 0x1000, v129
	global_load_dword v148, v130, s[84:85]
	global_load_dword v149, v130, s[84:85] offset:128
	v_add_u32_e32 v131, 0x1000, v130
	global_load_dword v150, v131, s[84:85]
	global_load_dword v151, v131, s[84:85] offset:128
	v_add_u32_e32 v132, 0x5000, v131
	global_load_dword v152, v132, s[84:85]
	global_load_dword v153, v132, s[84:85] offset:128
	v_add_u32_e32 v133, 0x1000, v132
	global_load_dword v154, v133, s[84:85]
	global_load_dword v155, v133, s[84:85] offset:128
	v_add_u32_e32 v134, 0x1000, v133
	global_load_dword v156, v134, s[84:85]
	global_load_dword v157, v134, s[84:85] offset:128
	v_add_u32_e32 v135, 0x1000, v134
	global_load_dword v158, v135, s[84:85]
	global_load_dword v159, v135, s[84:85] offset:128
	s_waitcnt vmcnt(32)
	v_add_f32_e32 v178, v120, v178
	v_add_f32_e32 v179, v104, v179
	global_store_dword v136, v178, s[84:85]
	global_store_dword v136, v179, s[84:85] offset:128
	v_add_f32_e32 v180, v121, v180
	v_add_f32_e32 v181, v105, v181
	global_store_dword v137, v180, s[84:85]
	global_store_dword v137, v181, s[84:85] offset:128
	v_add_f32_e32 v182, v122, v182
	v_add_f32_e32 v183, v106, v183
	global_store_dword v198, v182, s[84:85]
	global_store_dword v198, v183, s[84:85] offset:128
	v_add_f32_e32 v184, v123, v184
	v_add_f32_e32 v185, v107, v185
	global_store_dword v199, v184, s[84:85]
	global_store_dword v199, v185, s[84:85] offset:128
	v_add_f32_e32 v186, v124, v186
	v_add_f32_e32 v187, v108, v187
	global_store_dword v200, v186, s[84:85]
	global_store_dword v200, v187, s[84:85] offset:128
	v_add_f32_e32 v188, v125, v188
	v_add_f32_e32 v189, v109, v189
	global_store_dword v201, v188, s[84:85]
	global_store_dword v201, v189, s[84:85] offset:128
	v_add_f32_e32 v190, v126, v190
	v_add_f32_e32 v191, v110, v191
	global_store_dword v202, v190, s[84:85]
	global_store_dword v202, v191, s[84:85] offset:128
	v_add_f32_e32 v192, v127, v192
	v_add_f32_e32 v193, v111, v193
	global_store_dword v203, v192, s[84:85]
	global_store_dword v203, v193, s[84:85] offset:128
	v_add_u32_e32 v136, 0x5000, v135
	global_load_dword v178, v136, s[84:85]
	global_load_dword v179, v136, s[84:85] offset:128
	v_add_u32_e32 v137, 0x1000, v136
	global_load_dword v180, v137, s[84:85]
	global_load_dword v181, v137, s[84:85] offset:128
	v_add_u32_e32 v198, 0x1000, v137
	global_load_dword v182, v198, s[84:85]
	global_load_dword v183, v198, s[84:85] offset:128
	v_add_u32_e32 v199, 0x1000, v198
	global_load_dword v184, v199, s[84:85]
	global_load_dword v185, v199, s[84:85] offset:128
	v_add_u32_e32 v200, 0x5000, v199
	global_load_dword v186, v200, s[84:85]
	global_load_dword v187, v200, s[84:85] offset:128
	v_add_u32_e32 v201, 0x1000, v200
	global_load_dword v188, v201, s[84:85]
	global_load_dword v189, v201, s[84:85] offset:128
	v_add_u32_e32 v202, 0x1000, v201
	global_load_dword v190, v202, s[84:85]
	global_load_dword v191, v202, s[84:85] offset:128
	v_add_u32_e32 v203, 0x1000, v202
	global_load_dword v192, v203, s[84:85]
	global_load_dword v193, v203, s[84:85] offset:128
	s_waitcnt vmcnt(32)
	v_add_f32_e32 v144, v80, v144
	v_add_f32_e32 v145, v64, v145
	global_store_dword v128, v144, s[84:85]
	global_store_dword v128, v145, s[84:85] offset:128
	v_add_f32_e32 v146, v81, v146
	v_add_f32_e32 v147, v65, v147
	global_store_dword v129, v146, s[84:85]
	global_store_dword v129, v147, s[84:85] offset:128
	v_add_f32_e32 v148, v82, v148
	v_add_f32_e32 v149, v66, v149
	global_store_dword v130, v148, s[84:85]
	global_store_dword v130, v149, s[84:85] offset:128
	v_add_f32_e32 v150, v83, v150
	v_add_f32_e32 v151, v67, v151
	global_store_dword v131, v150, s[84:85]
	global_store_dword v131, v151, s[84:85] offset:128
	v_add_f32_e32 v152, v84, v152
	v_add_f32_e32 v153, v68, v153
	global_store_dword v132, v152, s[84:85]
	global_store_dword v132, v153, s[84:85] offset:128
	v_add_f32_e32 v154, v85, v154
	v_add_f32_e32 v155, v69, v155
	global_store_dword v133, v154, s[84:85]
	global_store_dword v133, v155, s[84:85] offset:128
	v_add_f32_e32 v156, v86, v156
	v_add_f32_e32 v157, v70, v157
	global_store_dword v134, v156, s[84:85]
	global_store_dword v134, v157, s[84:85] offset:128
	v_add_f32_e32 v158, v87, v158
	v_add_f32_e32 v159, v71, v159
	global_store_dword v135, v158, s[84:85]
	global_store_dword v135, v159, s[84:85] offset:128
	v_add_u32_e32 v128, 0x5000, v203
	global_load_dword v144, v128, s[84:85]
	global_load_dword v145, v128, s[84:85] offset:128
	v_add_u32_e32 v129, 0x1000, v128
	global_load_dword v146, v129, s[84:85]
	global_load_dword v147, v129, s[84:85] offset:128
	v_add_u32_e32 v130, 0x1000, v129
	global_load_dword v148, v130, s[84:85]
	global_load_dword v149, v130, s[84:85] offset:128
	v_add_u32_e32 v131, 0x1000, v130
	global_load_dword v150, v131, s[84:85]
	global_load_dword v151, v131, s[84:85] offset:128
	v_add_u32_e32 v132, 0x5000, v131
	global_load_dword v152, v132, s[84:85]
	global_load_dword v153, v132, s[84:85] offset:128
	v_add_u32_e32 v133, 0x1000, v132
	global_load_dword v154, v133, s[84:85]
	global_load_dword v155, v133, s[84:85] offset:128
	v_add_u32_e32 v134, 0x1000, v133
	global_load_dword v156, v134, s[84:85]
	global_load_dword v157, v134, s[84:85] offset:128
	v_add_u32_e32 v135, 0x1000, v134
	global_load_dword v158, v135, s[84:85]
	global_load_dword v159, v135, s[84:85] offset:128
	s_waitcnt vmcnt(32)
	v_add_f32_e32 v178, v88, v178
	v_add_f32_e32 v179, v72, v179
	global_store_dword v136, v178, s[84:85]
	global_store_dword v136, v179, s[84:85] offset:128
	v_add_f32_e32 v180, v89, v180
	v_add_f32_e32 v181, v73, v181
	global_store_dword v137, v180, s[84:85]
	global_store_dword v137, v181, s[84:85] offset:128
	v_add_f32_e32 v182, v90, v182
	v_add_f32_e32 v183, v74, v183
	global_store_dword v198, v182, s[84:85]
	global_store_dword v198, v183, s[84:85] offset:128
	v_add_f32_e32 v184, v91, v184
	v_add_f32_e32 v185, v75, v185
	global_store_dword v199, v184, s[84:85]
	global_store_dword v199, v185, s[84:85] offset:128
	v_add_f32_e32 v186, v92, v186
	v_add_f32_e32 v187, v76, v187
	global_store_dword v200, v186, s[84:85]
	global_store_dword v200, v187, s[84:85] offset:128
	v_add_f32_e32 v188, v93, v188
	v_add_f32_e32 v189, v77, v189
	global_store_dword v201, v188, s[84:85]
	global_store_dword v201, v189, s[84:85] offset:128
	v_add_f32_e32 v190, v94, v190
	v_add_f32_e32 v191, v78, v191
	global_store_dword v202, v190, s[84:85]
	global_store_dword v202, v191, s[84:85] offset:128
	v_add_f32_e32 v192, v95, v192
	v_add_f32_e32 v193, v79, v193
	global_store_dword v203, v192, s[84:85]
	global_store_dword v203, v193, s[84:85] offset:128
	v_add_u32_e32 v136, 0x5000, v135
	global_load_dword v178, v136, s[84:85]
	global_load_dword v179, v136, s[84:85] offset:128
	v_add_u32_e32 v137, 0x1000, v136
	global_load_dword v180, v137, s[84:85]
	global_load_dword v181, v137, s[84:85] offset:128
	v_add_u32_e32 v198, 0x1000, v137
	global_load_dword v182, v198, s[84:85]
	global_load_dword v183, v198, s[84:85] offset:128
	v_add_u32_e32 v199, 0x1000, v198
	global_load_dword v184, v199, s[84:85]
	global_load_dword v185, v199, s[84:85] offset:128
	v_add_u32_e32 v200, 0x5000, v199
	global_load_dword v186, v200, s[84:85]
	global_load_dword v187, v200, s[84:85] offset:128
	v_add_u32_e32 v201, 0x1000, v200
	global_load_dword v188, v201, s[84:85]
	global_load_dword v189, v201, s[84:85] offset:128
	v_add_u32_e32 v202, 0x1000, v201
	global_load_dword v190, v202, s[84:85]
	global_load_dword v191, v202, s[84:85] offset:128
	v_add_u32_e32 v203, 0x1000, v202
	global_load_dword v192, v203, s[84:85]
	global_load_dword v193, v203, s[84:85] offset:128
	s_waitcnt vmcnt(32)
	v_add_f32_e32 v144, v48, v144
	v_add_f32_e32 v145, v32, v145
	global_store_dword v128, v144, s[84:85]
	global_store_dword v128, v145, s[84:85] offset:128
	v_add_f32_e32 v146, v49, v146
	v_add_f32_e32 v147, v33, v147
	global_store_dword v129, v146, s[84:85]
	global_store_dword v129, v147, s[84:85] offset:128
	v_add_f32_e32 v148, v50, v148
	v_add_f32_e32 v149, v34, v149
	global_store_dword v130, v148, s[84:85]
	global_store_dword v130, v149, s[84:85] offset:128
	v_add_f32_e32 v150, v51, v150
	v_add_f32_e32 v151, v35, v151
	global_store_dword v131, v150, s[84:85]
	global_store_dword v131, v151, s[84:85] offset:128
	v_add_f32_e32 v152, v52, v152
	v_add_f32_e32 v153, v36, v153
	global_store_dword v132, v152, s[84:85]
	global_store_dword v132, v153, s[84:85] offset:128
	v_add_f32_e32 v154, v53, v154
	v_add_f32_e32 v155, v37, v155
	global_store_dword v133, v154, s[84:85]
	global_store_dword v133, v155, s[84:85] offset:128
	v_add_f32_e32 v156, v54, v156
	v_add_f32_e32 v157, v38, v157
	global_store_dword v134, v156, s[84:85]
	global_store_dword v134, v157, s[84:85] offset:128
	v_add_f32_e32 v158, v55, v158
	v_add_f32_e32 v159, v39, v159
	global_store_dword v135, v158, s[84:85]
	global_store_dword v135, v159, s[84:85] offset:128
	v_add_u32_e32 v128, 0x5000, v203
	global_load_dword v144, v128, s[84:85]
	global_load_dword v145, v128, s[84:85] offset:128
	v_add_u32_e32 v129, 0x1000, v128
	global_load_dword v146, v129, s[84:85]
	global_load_dword v147, v129, s[84:85] offset:128
	v_add_u32_e32 v130, 0x1000, v129
	global_load_dword v148, v130, s[84:85]
	global_load_dword v149, v130, s[84:85] offset:128
	v_add_u32_e32 v131, 0x1000, v130
	global_load_dword v150, v131, s[84:85]
	global_load_dword v151, v131, s[84:85] offset:128
	v_add_u32_e32 v132, 0x5000, v131
	global_load_dword v152, v132, s[84:85]
	global_load_dword v153, v132, s[84:85] offset:128
	v_add_u32_e32 v133, 0x1000, v132
	global_load_dword v154, v133, s[84:85]
	global_load_dword v155, v133, s[84:85] offset:128
	v_add_u32_e32 v134, 0x1000, v133
	global_load_dword v156, v134, s[84:85]
	global_load_dword v157, v134, s[84:85] offset:128
	v_add_u32_e32 v135, 0x1000, v134
	global_load_dword v158, v135, s[84:85]
	global_load_dword v159, v135, s[84:85] offset:128
	s_waitcnt vmcnt(32)
	v_add_f32_e32 v178, v56, v178
	v_add_f32_e32 v179, v40, v179
	global_store_dword v136, v178, s[84:85]
	global_store_dword v136, v179, s[84:85] offset:128
	v_add_f32_e32 v180, v57, v180
	v_add_f32_e32 v181, v41, v181
	global_store_dword v137, v180, s[84:85]
	global_store_dword v137, v181, s[84:85] offset:128
	v_add_f32_e32 v182, v58, v182
	v_add_f32_e32 v183, v42, v183
	global_store_dword v198, v182, s[84:85]
	global_store_dword v198, v183, s[84:85] offset:128
	v_add_f32_e32 v184, v59, v184
	v_add_f32_e32 v185, v43, v185
	global_store_dword v199, v184, s[84:85]
	global_store_dword v199, v185, s[84:85] offset:128
	v_add_f32_e32 v186, v60, v186
	v_add_f32_e32 v187, v44, v187
	global_store_dword v200, v186, s[84:85]
	global_store_dword v200, v187, s[84:85] offset:128
	v_add_f32_e32 v188, v61, v188
	v_add_f32_e32 v189, v45, v189
	global_store_dword v201, v188, s[84:85]
	global_store_dword v201, v189, s[84:85] offset:128
	v_add_f32_e32 v190, v62, v190
	v_add_f32_e32 v191, v46, v191
	global_store_dword v202, v190, s[84:85]
	global_store_dword v202, v191, s[84:85] offset:128
	v_add_f32_e32 v192, v63, v192
	v_add_f32_e32 v193, v47, v193
	global_store_dword v203, v192, s[84:85]
	global_store_dword v203, v193, s[84:85] offset:128
	v_add_u32_e32 v136, 0x5000, v135
	global_load_dword v178, v136, s[84:85]
	global_load_dword v179, v136, s[84:85] offset:128
	v_add_u32_e32 v137, 0x1000, v136
	global_load_dword v180, v137, s[84:85]
	global_load_dword v181, v137, s[84:85] offset:128
	v_add_u32_e32 v198, 0x1000, v137
	global_load_dword v182, v198, s[84:85]
	global_load_dword v183, v198, s[84:85] offset:128
	v_add_u32_e32 v199, 0x1000, v198
	global_load_dword v184, v199, s[84:85]
	global_load_dword v185, v199, s[84:85] offset:128
	v_add_u32_e32 v200, 0x5000, v199
	global_load_dword v186, v200, s[84:85]
	global_load_dword v187, v200, s[84:85] offset:128
	v_add_u32_e32 v201, 0x1000, v200
	global_load_dword v188, v201, s[84:85]
	global_load_dword v189, v201, s[84:85] offset:128
	v_add_u32_e32 v202, 0x1000, v201
	global_load_dword v190, v202, s[84:85]
	global_load_dword v191, v202, s[84:85] offset:128
	v_add_u32_e32 v203, 0x1000, v202
	global_load_dword v192, v203, s[84:85]
	global_load_dword v193, v203, s[84:85] offset:128
	s_waitcnt vmcnt(32)
	v_add_f32_e32 v144, v16, v144
	v_add_f32_e32 v145, v0, v145
	global_store_dword v128, v144, s[84:85]
	global_store_dword v128, v145, s[84:85] offset:128
	v_add_f32_e32 v146, v17, v146
	v_add_f32_e32 v147, v1, v147
	global_store_dword v129, v146, s[84:85]
	global_store_dword v129, v147, s[84:85] offset:128
	v_add_f32_e32 v148, v18, v148
	v_add_f32_e32 v149, v2, v149
	global_store_dword v130, v148, s[84:85]
	global_store_dword v130, v149, s[84:85] offset:128
	v_add_f32_e32 v150, v19, v150
	v_add_f32_e32 v151, v3, v151
	global_store_dword v131, v150, s[84:85]
	global_store_dword v131, v151, s[84:85] offset:128
	v_add_f32_e32 v152, v20, v152
	v_add_f32_e32 v153, v4, v153
	global_store_dword v132, v152, s[84:85]
	global_store_dword v132, v153, s[84:85] offset:128
	v_add_f32_e32 v154, v21, v154
	v_add_f32_e32 v155, v5, v155
	global_store_dword v133, v154, s[84:85]
	global_store_dword v133, v155, s[84:85] offset:128
	v_add_f32_e32 v156, v22, v156
	v_add_f32_e32 v157, v6, v157
	global_store_dword v134, v156, s[84:85]
	global_store_dword v134, v157, s[84:85] offset:128
	v_add_f32_e32 v158, v23, v158
	v_add_f32_e32 v159, v7, v159
	global_store_dword v135, v158, s[84:85]
	global_store_dword v135, v159, s[84:85] offset:128
	s_waitcnt vmcnt(16)
	v_add_f32_e32 v178, v24, v178
	v_add_f32_e32 v179, v8, v179
	global_store_dword v136, v178, s[84:85]
	global_store_dword v136, v179, s[84:85] offset:128
	v_add_f32_e32 v180, v25, v180
	v_add_f32_e32 v181, v9, v181
	global_store_dword v137, v180, s[84:85]
	global_store_dword v137, v181, s[84:85] offset:128
	v_add_f32_e32 v182, v26, v182
	v_add_f32_e32 v183, v10, v183
	global_store_dword v198, v182, s[84:85]
	global_store_dword v198, v183, s[84:85] offset:128
	v_add_f32_e32 v184, v27, v184
	v_add_f32_e32 v185, v11, v185
	global_store_dword v199, v184, s[84:85]
	global_store_dword v199, v185, s[84:85] offset:128
	v_add_f32_e32 v186, v28, v186
	v_add_f32_e32 v187, v12, v187
	global_store_dword v200, v186, s[84:85]
	global_store_dword v200, v187, s[84:85] offset:128
	v_add_f32_e32 v188, v29, v188
	v_add_f32_e32 v189, v13, v189
	global_store_dword v201, v188, s[84:85]
	global_store_dword v201, v189, s[84:85] offset:128
	v_add_f32_e32 v190, v30, v190
	v_add_f32_e32 v191, v14, v191
	global_store_dword v202, v190, s[84:85]
	global_store_dword v202, v191, s[84:85] offset:128
	v_add_f32_e32 v192, v31, v192
	v_add_f32_e32 v193, v15, v193
	global_store_dword v203, v192, s[84:85]
	global_store_dword v203, v193, s[84:85] offset:128
	s_cmpk_lt_i32 s2, 0x100
	s_cbranch_scc1 .LBB0_991
	v_readlane_b32 s16, v252, 39
